# speedup vs baseline: 1.0070x; 1.0070x over previous
;     ...
;   for (int k0 = 0; k0 < K; k0 += 128) {
;     G_READ(fa1, fb1, 0, 32);
;     if (k0 + 128 < K) G_LOAD(ra0, rb0, k0 + 128);
;     __builtin_amdgcn_sched_barrier(0);
;     G_MFMA_ST(fa0, fb0, ra1, rb1, 1);
;     __syncthreads();
;     G_READ(fa0, fb0, 1, 0);
;     __builtin_amdgcn_sched_barrier(0);
;     G_MFMA(fa1, fb1);
;     __builtin_amdgcn_sched_barrier(0);
;     G_READ(fa1, fb1, 1, 32);
;     if (k0 + 192 < K) G_LOAD(ra1, rb1, k0 + 192);
;     __builtin_amdgcn_sched_barrier(0);
;     if (k0 + 128 < K) {
;       G_MFMA_ST(fa0, fb0, ra0, rb0, 0);
;       __syncthreads();
;       G_READ(fa0, fb0, 0, 0);
;     } else {
;       G_MFMA(fa0, fb0);
;     }
;     __builtin_amdgcn_sched_barrier(0);
;     G_MFMA(fa1, fb1);
;     __builtin_amdgcn_sched_barrier(0);
;   }
; __device__ __forceinline__ void phase_inproj(const Params& p, const int tidx) {
;     ...
;   for (int tile = blockIdx.x, rnd = 0; tile < 128 * NTN; tile += gridDim.x, rnd++) {
;     int mt = tile / NTN, nt = tile % NTN;
;     if (swz) {
;       int j = rnd * 32 + li;
;       int g = j / (4 * NTN), rem = j % (4 * NTN);
;       nt = rem >> 2;
;       mt = xcd * 16 + g * 4 + (rem & 3);
;     }
;     f32x4 acc[4][4];
;     zero_acc<4>(acc);
;     gemm_main<4, 1024>(acc, H + (size_t)mt * 256 * 1024, 1024, W + (size_t)nt * 128 * 1024, 1024, sA, sB, tidx);
.Lip_pf_go:
	s_ashr_i32 s99, s98, 31
	s_lshl_b64 s[60:61], s[98:99], 19
	s_add_u32 s60, s50, s60
	s_addc_u32 s61, s51, s61
	s_ashr_i32 s43, s42, 31
	s_lshl_b64 s[62:63], s[42:43], 18
	v_readlane_b32 s98, v251, 20
	v_readlane_b32 s99, v251, 21
	s_add_u32 s62, s98, s62
	s_addc_u32 s63, s99, s63
	global_load_dword v151, v171, s[62:63]
	v_mfma_f32_16x16x32_bf16 v[126:129], v[214:217], v[174:177], v[126:129]
	v_mfma_f32_16x16x32_bf16 v[130:133], v[218:221], v[174:177], v[130:133]
	v_mfma_f32_16x16x32_bf16 v[134:137], v[222:225], v[174:177], v[134:137]
	v_mfma_f32_16x16x32_bf16 v[42:45], v[226:229], v[174:177], v[42:45]
	v_mfma_f32_16x16x32_bf16 v[58:61], v[214:217], v[178:181], v[58:61]
	v_mfma_f32_16x16x32_bf16 v[62:65], v[218:221], v[178:181], v[62:65]
	v_mfma_f32_16x16x32_bf16 v[74:77], v[222:225], v[178:181], v[74:77]
	v_mfma_f32_16x16x32_bf16 v[46:49], v[226:229], v[178:181], v[46:49]
	v_mfma_f32_16x16x32_bf16 v[66:69], v[214:217], v[206:209], v[66:69]
	v_mfma_f32_16x16x32_bf16 v[78:81], v[218:221], v[206:209], v[78:81]
	v_mfma_f32_16x16x32_bf16 v[82:85], v[222:225], v[206:209], v[82:85]
	v_mfma_f32_16x16x32_bf16 v[50:53], v[226:229], v[206:209], v[50:53]
	v_mfma_f32_16x16x32_bf16 v[70:73], v[214:217], v[210:213], v[70:73]
	v_mfma_f32_16x16x32_bf16 v[86:89], v[218:221], v[210:213], v[86:89]
	v_mfma_f32_16x16x32_bf16 v[90:93], v[222:225], v[210:213], v[90:93]
	v_mfma_f32_16x16x32_bf16 v[54:57], v[226:229], v[210:213], v[54:57]
	ds_read_b128 v[174:177], v30 offset:64
	ds_read_b128 v[178:181], v30 offset:2624
	ds_read_b128 v[182:185], v30 offset:5184
	ds_read_b128 v[186:189], v30 offset:7744
	ds_read_b128 v[190:193], v31 offset:41024
	ds_read_b128 v[194:197], v31 offset:43584
	ds_read_b128 v[198:201], v31 offset:46144
	ds_read_b128 v[202:205], v31 offset:48704
	s_waitcnt lgkmcnt(11)
	v_mfma_f32_16x16x32_bf16 v[126:129], v[110:113], v[94:97], v[126:129]
	s_waitcnt vmcnt(6)
	ds_write_b128 v22, v[138:141] offset:61440
	s_waitcnt vmcnt(2)
	ds_write_b128 v23, v[12:15] offset:61440
	s_waitcnt lgkmcnt(12)
	v_mfma_f32_16x16x32_bf16 v[130:133], v[114:117], v[94:97], v[130:133]
	s_waitcnt lgkmcnt(11)
	v_mfma_f32_16x16x32_bf16 v[134:137], v[118:121], v[94:97], v[134:137]
	s_waitcnt lgkmcnt(10)
	v_mfma_f32_16x16x32_bf16 v[12:15], v[122:125], v[94:97], v[42:45]
	v_mfma_f32_16x16x32_bf16 v[42:45], v[110:113], v[98:101], v[58:61]
	ds_write_b128 v24, v[142:145] offset:61440
	s_waitcnt vmcnt(1)
	ds_write_b128 v25, v[156:159] offset:61440
	v_mfma_f32_16x16x32_bf16 v[58:61], v[114:117], v[98:101], v[62:65]
	v_mfma_f32_16x16x32_bf16 v[62:65], v[118:121], v[98:101], v[74:77]
	v_mfma_f32_16x16x32_bf16 v[46:49], v[122:125], v[98:101], v[46:49]
	v_mfma_f32_16x16x32_bf16 v[66:69], v[110:113], v[102:105], v[66:69]
	ds_write_b128 v26, v[8:11] offset:61440
	v_mfma_f32_16x16x32_bf16 v[74:77], v[114:117], v[102:105], v[78:81]
	v_mfma_f32_16x16x32_bf16 v[78:81], v[118:121], v[102:105], v[82:85]
	v_mfma_f32_16x16x32_bf16 v[8:11], v[122:125], v[102:105], v[50:53]
	v_mfma_f32_16x16x32_bf16 v[50:53], v[110:113], v[106:109], v[70:73]
	ds_write_b128 v27, v[152:155] offset:61440
	v_mfma_f32_16x16x32_bf16 v[70:73], v[114:117], v[106:109], v[86:89]
	v_mfma_f32_16x16x32_bf16 v[82:85], v[118:121], v[106:109], v[90:93]
	v_mfma_f32_16x16x32_bf16 v[54:57], v[122:125], v[106:109], v[54:57]
	s_waitcnt lgkmcnt(0)
	s_barrier
	ds_read_b128 v[86:89], v39 offset:61440
	ds_read_b128 v[90:93], v39 offset:64000
	ds_read_b128 v[94:97], v32 offset:5120
	ds_read_b128 v[98:101], v32 offset:7680
	ds_read_b128 v[102:105], v33
	ds_read_b128 v[106:109], v33 offset:2560
	ds_read_b128 v[110:113], v33 offset:5120
	ds_read_b128 v[114:117], v33 offset:7680
	v_mfma_f32_16x16x32_bf16 v[118:121], v[190:193], v[174:177], v[126:129]
	v_mfma_f32_16x16x32_bf16 v[122:125], v[194:197], v[174:177], v[130:133]
	v_mfma_f32_16x16x32_bf16 v[126:129], v[198:201], v[174:177], v[134:137]
	v_mfma_f32_16x16x32_bf16 v[12:15], v[202:205], v[174:177], v[12:15]
	v_mfma_f32_16x16x32_bf16 v[42:45], v[190:193], v[178:181], v[42:45]
	v_mfma_f32_16x16x32_bf16 v[58:61], v[194:197], v[178:181], v[58:61]
	v_mfma_f32_16x16x32_bf16 v[62:65], v[198:201], v[178:181], v[62:65]
	v_mfma_f32_16x16x32_bf16 v[46:49], v[202:205], v[178:181], v[46:49]
	v_mfma_f32_16x16x32_bf16 v[66:69], v[190:193], v[182:185], v[66:69]
	v_mfma_f32_16x16x32_bf16 v[74:77], v[194:197], v[182:185], v[74:77]
	v_mfma_f32_16x16x32_bf16 v[78:81], v[198:201], v[182:185], v[78:81]
	v_mfma_f32_16x16x32_bf16 v[8:11], v[202:205], v[182:185], v[8:11]
	v_mfma_f32_16x16x32_bf16 v[50:53], v[190:193], v[186:189], v[50:53]
	v_mfma_f32_16x16x32_bf16 v[70:73], v[194:197], v[186:189], v[70:73]
	v_mfma_f32_16x16x32_bf16 v[82:85], v[198:201], v[186:189], v[82:85]
	v_mfma_f32_16x16x32_bf16 v[54:57], v[202:205], v[186:189], v[54:57]
	ds_read_b128 v[130:133], v30 offset:61504
	ds_read_b128 v[134:137], v30 offset:64064
	ds_read_b128 v[138:141], v34 offset:64
	ds_read_b128 v[142:145], v35 offset:64
	ds_read_b128 v[152:155], v41 offset:64
	ds_read_b128 v[156:159], v36 offset:64
	ds_read_b128 v[174:177], v37 offset:64
	ds_read_b128 v[178:181], v38 offset:64
	s_waitcnt lgkmcnt(11)
	v_mfma_f32_16x16x32_bf16 v[118:121], v[102:105], v[86:89], v[118:121]
	s_waitcnt lgkmcnt(10)
	v_mfma_f32_16x16x32_bf16 v[122:125], v[106:109], v[86:89], v[122:125]
	s_waitcnt lgkmcnt(9)
	v_mfma_f32_16x16x32_bf16 v[126:129], v[110:113], v[86:89], v[126:129]
	s_waitcnt lgkmcnt(8)
; template <int TN, bool NTS = false>
; __device__ __forceinline__ void store_tile_bf16(const f32x4 (&acc)[4][TN], bf16_t* __restrict__ dst, int ldd, bf16_t* sT,
;                                                 const int tidx) {
;   constexpr int BN = 32 * TN, TS = BN + 8, CPR = BN / 8;
;   const int lane = tidx & 63, w = tidx >> 6;
;   const int wm = w >> 1, wn = w & 1, l15 = lane & 15, quad = lane >> 4;
;   __syncthreads();
; #pragma unroll
;   for (int i = 0; i < 4; i++)
; #pragma unroll
;     for (int j = 0; j < TN; j++)
; #pragma unroll
;       for (int r = 0; r < 4; r++)
;         sT[(wm * 64 + i * 16 + quad * 4 + r) * TS + wn * TN * 16 + j * 16 + l15] = f2bf(acc[i][j][r]);
;   __syncthreads();
; #pragma unroll
;   for (int c = tidx; c < 256 * CPR; c += NT) {
;     int row = c / CPR, cc = c % CPR;
;     const u32x4 v_ = *(const u32x4*)(sT + row * TS + cc * 8);
;     if (NTS) __builtin_nontemporal_store(v_, (u32x4*)(dst + (size_t)row * ldd + cc * 8));
;     else *(u32x4*)(dst + (size_t)row * ldd + cc * 8) = v_;
;   }
	v_mfma_f32_16x16x32_bf16 v[12:15], v[114:117], v[86:89], v[12:15]
	v_mfma_f32_16x16x32_bf16 v[40:43], v[102:105], v[90:93], v[42:45]
	v_mfma_f32_16x16x32_bf16 v[58:61], v[106:109], v[90:93], v[58:61]
	v_mfma_f32_16x16x32_bf16 v[62:65], v[110:113], v[90:93], v[62:65]
	v_mfma_f32_16x16x32_bf16 v[44:47], v[114:117], v[90:93], v[46:49]
	v_mfma_f32_16x16x32_bf16 v[66:69], v[102:105], v[94:97], v[66:69]
	v_mfma_f32_16x16x32_bf16 v[74:77], v[106:109], v[94:97], v[74:77]
	v_mfma_f32_16x16x32_bf16 v[78:81], v[110:113], v[94:97], v[78:81]
	v_mfma_f32_16x16x32_bf16 v[8:11], v[114:117], v[94:97], v[8:11]
	v_mfma_f32_16x16x32_bf16 v[48:51], v[102:105], v[98:101], v[50:53]
	v_mfma_f32_16x16x32_bf16 v[70:73], v[106:109], v[98:101], v[70:73]
	v_mfma_f32_16x16x32_bf16 v[82:85], v[110:113], v[98:101], v[82:85]
	v_mfma_f32_16x16x32_bf16 v[52:55], v[114:117], v[98:101], v[54:57]
	s_waitcnt lgkmcnt(3)
	v_mfma_f32_16x16x32_bf16 v[86:89], v[152:155], v[130:133], v[118:121]
	s_waitcnt lgkmcnt(2)
	v_mfma_f32_16x16x32_bf16 v[90:93], v[156:159], v[130:133], v[122:125]
	s_waitcnt lgkmcnt(1)
	v_mfma_f32_16x16x32_bf16 v[94:97], v[174:177], v[130:133], v[126:129]
	s_waitcnt lgkmcnt(0)
	v_mfma_f32_16x16x32_bf16 v[12:15], v[178:181], v[130:133], v[12:15]
	v_mfma_f32_16x16x32_bf16 v[40:43], v[152:155], v[134:137], v[40:43]
	v_mfma_f32_16x16x32_bf16 v[56:59], v[156:159], v[134:137], v[58:61]
	v_mfma_f32_16x16x32_bf16 v[60:63], v[174:177], v[134:137], v[62:65]
	v_mfma_f32_16x16x32_bf16 v[44:47], v[178:181], v[134:137], v[44:47]
	v_mfma_f32_16x16x32_bf16 v[64:67], v[152:155], v[138:141], v[66:69]
	v_mfma_f32_16x16x32_bf16 v[74:77], v[156:159], v[138:141], v[74:77]
	v_mfma_f32_16x16x32_bf16 v[78:81], v[174:177], v[138:141], v[78:81]
	v_mfma_f32_16x16x32_bf16 v[8:11], v[178:181], v[138:141], v[8:11]
	v_mfma_f32_16x16x32_bf16 v[48:51], v[152:155], v[142:145], v[48:51]
	v_mfma_f32_16x16x32_bf16 v[68:71], v[156:159], v[142:145], v[70:73]
	v_mfma_f32_16x16x32_bf16 v[82:85], v[174:177], v[142:145], v[82:85]
	v_mfma_f32_16x16x32_bf16 v[52:55], v[178:181], v[142:145], v[52:55]
	s_mul_hi_i32 s13, s14, 0x3a0000
	s_mul_i32 s14, s14, 0x3a0000
	s_add_u32 s14, s94, s14
	s_addc_u32 s15, s95, s13
	s_lshl_b32 s12, s12, 8
	s_add_u32 s12, s14, s12
	s_addc_u32 s13, s15, 0
	v_lshrrev_b32_e32 v2, 7, v150
	v_and_b32_e32 v3, 7, v150
	v_lshl_or_b32 v2, v2, 6, v3
	v_mul_u32_u24_e32 v2, 0x3a00, v2
	v_bfe_u32 v3, v150, 6, 1
	v_bfe_u32 v16, v150, 3, 1
	v_lshl_or_b32 v3, v3, 1, v16
	v_bfe_u32 v16, v150, 4, 2
	v_lshl_or_b32 v3, v3, 2, v16
	v_lshl_add_u32 v2, v3, 4, v2
	v_add_u32_e32 v3, 0x1d000, v2
	v_cvt_pk_bf16_f32 v86, v86, v87
	v_cvt_pk_bf16_f32 v87, v88, v89
	v_cvt_pk_bf16_f32 v88, v90, v91
	v_cvt_pk_bf16_f32 v89, v92, v93
	v_cvt_pk_bf16_f32 v94, v94, v95
	v_cvt_pk_bf16_f32 v95, v96, v97
	v_cvt_pk_bf16_f32 v96, v12, v13
	v_cvt_pk_bf16_f32 v97, v14, v15
	v_mov_b32_e32 v90, v86
	v_mov_b32_e32 v91, v87
	v_mov_b32_e32 v92, v88
	v_mov_b32_e32 v93, v89
	v_mov_b32_dpp v86, v94 row_ror:8 row_mask:0xf bank_mask:0xc
	v_mov_b32_dpp v87, v95 row_ror:8 row_mask:0xf bank_mask:0xc
	v_mov_b32_dpp v88, v96 row_ror:8 row_mask:0xf bank_mask:0xc
	v_mov_b32_dpp v89, v97 row_ror:8 row_mask:0xf bank_mask:0xc
	v_mov_b32_dpp v94, v90 row_ror:8 row_mask:0xf bank_mask:0x3
	v_mov_b32_dpp v95, v91 row_ror:8 row_mask:0xf bank_mask:0x3
	v_mov_b32_dpp v96, v92 row_ror:8 row_mask:0xf bank_mask:0x3
	v_mov_b32_dpp v97, v93 row_ror:8 row_mask:0xf bank_mask:0x3
	global_store_dwordx4 v2, v[86:89], s[12:13] nt
	global_store_dwordx4 v3, v[94:97], s[12:13] nt
	s_add_u32 s12, s12, 0x3a000
	s_addc_u32 s13, s13, 0
	v_cvt_pk_bf16_f32 v40, v40, v41
	v_cvt_pk_bf16_f32 v41, v42, v43
	v_cvt_pk_bf16_f32 v42, v56, v57
	v_cvt_pk_bf16_f32 v43, v58, v59
	v_cvt_pk_bf16_f32 v60, v60, v61
	v_cvt_pk_bf16_f32 v61, v62, v63
	v_cvt_pk_bf16_f32 v62, v44, v45
	v_cvt_pk_bf16_f32 v63, v46, v47
	v_mov_b32_e32 v56, v40
	v_mov_b32_e32 v57, v41
	v_mov_b32_e32 v58, v42
	v_mov_b32_e32 v59, v43
	v_mov_b32_dpp v40, v60 row_ror:8 row_mask:0xf bank_mask:0xc
	v_mov_b32_dpp v41, v61 row_ror:8 row_mask:0xf bank_mask:0xc
	v_mov_b32_dpp v42, v62 row_ror:8 row_mask:0xf bank_mask:0xc
	v_mov_b32_dpp v43, v63 row_ror:8 row_mask:0xf bank_mask:0xc
	v_mov_b32_dpp v60, v56 row_ror:8 row_mask:0xf bank_mask:0x3
	v_mov_b32_dpp v61, v57 row_ror:8 row_mask:0xf bank_mask:0x3
	v_mov_b32_dpp v62, v58 row_ror:8 row_mask:0xf bank_mask:0x3
	v_mov_b32_dpp v63, v59 row_ror:8 row_mask:0xf bank_mask:0x3
	global_store_dwordx4 v2, v[40:43], s[12:13] nt
	global_store_dwordx4 v3, v[60:63], s[12:13] nt
	s_add_u32 s12, s12, 0x3a000
	s_addc_u32 s13, s13, 0
	v_cvt_pk_bf16_f32 v64, v64, v65
	v_cvt_pk_bf16_f32 v65, v66, v67
	v_cvt_pk_bf16_f32 v66, v74, v75
	v_cvt_pk_bf16_f32 v67, v76, v77
	v_cvt_pk_bf16_f32 v78, v78, v79
	v_cvt_pk_bf16_f32 v79, v80, v81
	v_cvt_pk_bf16_f32 v80, v8, v9
	v_cvt_pk_bf16_f32 v81, v10, v11
	v_mov_b32_e32 v74, v64
	v_mov_b32_e32 v75, v65
	v_mov_b32_e32 v76, v66
	v_mov_b32_e32 v77, v67
	v_mov_b32_dpp v64, v78 row_ror:8 row_mask:0xf bank_mask:0xc
	v_mov_b32_dpp v65, v79 row_ror:8 row_mask:0xf bank_mask:0xc
	v_mov_b32_dpp v66, v80 row_ror:8 row_mask:0xf bank_mask:0xc
	v_mov_b32_dpp v67, v81 row_ror:8 row_mask:0xf bank_mask:0xc
	v_mov_b32_dpp v78, v74 row_ror:8 row_mask:0xf bank_mask:0x3
	v_mov_b32_dpp v79, v75 row_ror:8 row_mask:0xf bank_mask:0x3
	v_mov_b32_dpp v80, v76 row_ror:8 row_mask:0xf bank_mask:0x3
	v_mov_b32_dpp v81, v77 row_ror:8 row_mask:0xf bank_mask:0x3
	global_store_dwordx4 v2, v[64:67], s[12:13] nt
	global_store_dwordx4 v3, v[78:81], s[12:13] nt
	s_add_u32 s12, s12, 0x3a000
	s_addc_u32 s13, s13, 0
	v_cvt_pk_bf16_f32 v48, v48, v49
	v_cvt_pk_bf16_f32 v49, v50, v51
	v_cvt_pk_bf16_f32 v50, v68, v69
	v_cvt_pk_bf16_f32 v51, v70, v71
	v_cvt_pk_bf16_f32 v82, v82, v83
	v_cvt_pk_bf16_f32 v83, v84, v85
	v_cvt_pk_bf16_f32 v84, v52, v53
	v_cvt_pk_bf16_f32 v85, v54, v55
	v_mov_b32_e32 v68, v48
	v_mov_b32_e32 v69, v49
	v_mov_b32_e32 v70, v50
	v_mov_b32_e32 v71, v51
	v_mov_b32_dpp v48, v82 row_ror:8 row_mask:0xf bank_mask:0xc
	v_mov_b32_dpp v49, v83 row_ror:8 row_mask:0xf bank_mask:0xc
	v_mov_b32_dpp v50, v84 row_ror:8 row_mask:0xf bank_mask:0xc
	v_mov_b32_dpp v51, v85 row_ror:8 row_mask:0xf bank_mask:0xc
	v_mov_b32_dpp v82, v68 row_ror:8 row_mask:0xf bank_mask:0x3
	v_mov_b32_dpp v83, v69 row_ror:8 row_mask:0xf bank_mask:0x3
	v_mov_b32_dpp v84, v70 row_ror:8 row_mask:0xf bank_mask:0x3
	v_mov_b32_dpp v85, v71 row_ror:8 row_mask:0xf bank_mask:0x3
	global_store_dwordx4 v2, v[48:51], s[12:13] nt
	global_store_dwordx4 v3, v[82:85], s[12:13] nt
	s_branch .LBB0_581
